# ret_out cross-item software pipeline: next item's six staging loads issued after this item's operand prefetch (counted waits +6)
# speedup vs baseline: 1.0151x; 1.0024x over previous
.Lro_compute:
	s_or_b32 s0, s14, s22
	s_lshl_b64 s[2:3], s[0:1], 2
	s_add_u32 s2, s48, s2
	s_addc_u32 s3, s49, s3
	s_waitcnt lgkmcnt(0)
	s_barrier
	global_load_dword v2, v193, s[2:3]
	global_load_dword v3, v193, s[2:3] offset:16
	s_mov_b32 s0, 0xbfb8aa3b
	s_mov_b32 s2, 0x42ce8ed0
	s_mov_b32 s3, 0x33800000
	v_add_u32_e32 v34, vcc_lo, v38
	v_ashrrev_i32_e32 v35, 31, v34
	v_lshlrev_b64 v[36:37], 9, v[34:35]
	v_lshlrev_b32_e32 v192, 1, v32
	v_lshlrev_b64 v[34:35], 11, v[34:35]
	v_readlane_b32 s98, v254, 15
	v_readlane_b32 s99, v254, 16
	v_readlane_b32 s100, v254, 19
	v_readlane_b32 s101, v254, 20
	v_or_b32_e32 v172, v109, v32
	v_mov_b32_e32 v173, 0
	v_lshl_add_u64 v[174:175], s[98:99], 0, v[36:37]
	v_lshl_add_u64 v[174:175], v[0:1], 1, v[174:175]
	v_lshl_add_u64 v[174:175], v[174:175], 0, v[192:193]
	global_load_dwordx4 v[176:179], v[174:175], off
	global_load_dwordx4 v[180:183], v[174:175], off offset:64
	v_lshl_add_u64 v[174:175], s[100:101], 0, v[36:37]
	v_lshl_add_u64 v[174:175], v[172:173], 1, v[174:175]
	global_load_dwordx4 v[184:187], v[174:175], off
	global_load_dwordx4 v[188:191], v[174:175], off offset:64
	v_lshl_add_u64 v[174:175], v[172:173], 2, s[92:93]
	global_load_dwordx4 v[208:211], v[174:175], off
	global_load_dwordx4 v[212:215], v[174:175], off offset:16
	global_load_dwordx4 v[216:219], v[174:175], off offset:128
	global_load_dwordx4 v[244:247], v[174:175], off offset:144
	v_readlane_b32 s98, v253, 0
	s_nop 1
	s_add_i32 s98, s97, s98
	s_cmpk_gt_i32 s98, 0x9ff
	s_cbranch_scc1 .Lro_last
	s_lshl_b32 s99, s98, 5
	s_and_b32 s99, s99, 0xffffff80
	s_lshl_b32 s99, s99, 9
	v_readlane_b32 s100, v254, 17
	v_readlane_b32 s101, v254, 18
	s_nop 1
	s_add_u32 s100, s100, s99
	s_addc_u32 s101, s101, 0
	s_and_b32 s99, s97, 3
	s_lshl_b32 s99, s99, 7
	s_add_u32 s100, s100, s99
	s_addc_u32 s101, s101, 0
	s_nop 2
	global_load_dwordx4 v[148:151], v146, s[100:101]
	global_load_dwordx4 v[152:155], v147, s[100:101]
	s_lshl_b32 s99, s98, 5
	s_and_b32 s99, s99, 0xffffff80
	s_lshl_b32 s99, s99, 1
	v_readlane_b32 s100, v253, 54
	v_readlane_b32 s101, v253, 55
	s_nop 1
	s_add_u32 s100, s100, s99
	s_addc_u32 s101, s101, 0
	s_nop 4
	global_load_dwordx4 v[156:159], v206, s[100:101]
	global_load_dwordx4 v[160:163], v207, s[100:101]
	v_readlane_b32 s100, v254, 6
	v_readlane_b32 s101, v254, 7
	s_lshl_b32 s99, s98, 14
	s_add_u32 s100, s100, s99
	s_addc_u32 s101, s101, 0
	s_nop 4
	global_load_dwordx4 v[164:167], v248, s[100:101]
	global_load_dwordx4 v[168:171], v249, s[100:101]
	s_branch .Lro_pfd
.Lro_last:
	v_readlane_b32 s100, v254, 17
	v_readlane_b32 s101, v254, 18
	s_nop 4
	global_load_dwordx4 v[148:151], v146, s[100:101]
	global_load_dwordx4 v[152:155], v146, s[100:101]
	global_load_dwordx4 v[156:159], v146, s[100:101]
	global_load_dwordx4 v[160:163], v146, s[100:101]
	global_load_dwordx4 v[164:167], v146, s[100:101]
	global_load_dwordx4 v[168:171], v146, s[100:101]
.Lro_pfd:
	s_waitcnt vmcnt(15)
	v_mul_f32_e32 v4, 0xbfb8aa3b, v2
	v_fma_f32 v5, v2, s0, -v4
	v_rndne_f32_e32 v6, v4
	v_fmac_f32_e32 v5, 0xb2a5705f, v2
	v_sub_f32_e32 v4, v4, v6
	v_add_f32_e32 v4, v4, v5
	v_cvt_i32_f32_e32 v6, v6
	v_exp_f32_e32 v4, v4
	s_waitcnt vmcnt(14)
	v_mul_f32_e32 v5, 0xbfb8aa3b, v3
	v_rndne_f32_e32 v7, v5
	v_cmp_nlt_f32_e64 s[68:69], s2, v2
	v_ldexp_f32 v4, v4, v6
	v_fma_f32 v6, v3, s0, -v5
	v_fmac_f32_e32 v6, 0xb2a5705f, v3
	v_sub_f32_e32 v5, v5, v7
	v_add_f32_e32 v5, v5, v6
	v_cvt_i32_f32_e32 v7, v7
	v_exp_f32_e32 v5, v5
	v_cndmask_b32_e64 v4, 0, v4, s[68:69]
	v_cmp_nlt_f32_e64 s[68:69], s2, v3
	s_mov_b32 s0, 0xc2b17218
	v_ldexp_f32 v5, v5, v7
	v_cndmask_b32_e64 v5, 0, v5, s[68:69]
	v_cmp_ngt_f32_e64 s[68:69], s0, v2
	s_mov_b32 s2, 0x3f317218
	s_nop 0
	v_cndmask_b32_e64 v18, v224, v4, s[68:69]
	v_cmp_ngt_f32_e64 s[68:69], s0, v3
	v_add_f32_e32 v4, 1.0, v18
	v_cvt_f64_f32_e32 v[2:3], v4
	v_cndmask_b32_e64 v19, v224, v5, s[68:69]
	v_frexp_mant_f32_e32 v5, v4
	s_mov_b32 s0, 0x3f2aaaab
	v_frexp_exp_i32_f64_e32 v2, v[2:3]
	v_cmp_gt_f32_e64 s[68:69], s0, v5
	v_add_f32_e32 v20, 1.0, v19
	v_frexp_mant_f32_e32 v6, v20
	v_subbrev_co_u32_e64 v5, s[68:69], 0, v2, s[68:69]
	v_cvt_f64_f32_e32 v[2:3], v20
	v_frexp_exp_i32_f64_e32 v2, v[2:3]
	v_cmp_gt_f32_e64 s[68:69], s0, v6
	v_sub_u32_e32 v6, 0, v5
	s_mov_b32 s0, 0x7f800000
	v_subbrev_co_u32_e64 v21, s[68:69], 0, v2, s[68:69]
	v_add_f32_e32 v2, -1.0, v4
	v_sub_f32_e32 v3, v2, v4
	v_sub_f32_e32 v2, v18, v2
	v_add_f32_e32 v3, 1.0, v3
	v_add_f32_e32 v3, v2, v3
	v_ldexp_f32 v4, v4, v6
	v_ldexp_f32 v3, v3, v6
	v_add_f32_e32 v6, -1.0, v4
	v_add_f32_e32 v7, 1.0, v4
	v_cvt_f32_i32_e32 v2, v5
	v_add_f32_e32 v5, 1.0, v6
	v_add_f32_e32 v8, -1.0, v7
	v_sub_f32_e32 v5, v4, v5
	v_sub_f32_e32 v4, v4, v8
	v_add_f32_e32 v8, v3, v5
	v_add_f32_e32 v3, v3, v4
	v_add_f32_e32 v10, v7, v3
	v_rcp_f32_e32 v11, v10
	v_add_f32_e32 v5, v6, v8
	v_sub_f32_e32 v6, v6, v5
	v_sub_f32_e32 v4, v7, v10
	v_mul_f32_e32 v13, v5, v11
	v_add_f32_e32 v12, v8, v6
	v_mul_f32_e32 v6, v10, v13
	v_add_f32_e32 v3, v3, v4
	v_fma_f32 v8, v13, v10, -v6
	v_fmac_f32_e32 v8, v13, v3
	v_add_f32_e32 v4, v6, v8
	v_sub_f32_e32 v7, v5, v4
	v_mov_b32_e32 v9, v4
	v_pk_add_f32 v[4:5], v[4:5], v[6:7] neg_lo:[0,1] neg_hi:[0,1]
	v_cmp_neq_f32_e64 s[68:69], s0, v18
	v_pk_add_f32 v[4:5], v[4:5], v[8:9] neg_lo:[0,1] neg_hi:[0,1]
	s_nop 0
	v_add_f32_e32 v5, v12, v5
	v_add_f32_e32 v4, v4, v5
	v_add_f32_e32 v5, v7, v4
	v_mul_f32_e32 v9, v11, v5
	v_mul_f32_e32 v6, v10, v9
	v_sub_f32_e32 v7, v7, v5
	v_add_f32_e32 v14, v13, v9
	v_fma_f32 v8, v9, v10, -v6
	v_add_f32_e32 v12, v4, v7
	v_sub_f32_e32 v4, v14, v13
	v_fmac_f32_e32 v8, v9, v3
	v_sub_f32_e32 v3, v9, v4
	v_add_f32_e32 v4, v6, v8
	v_sub_f32_e32 v7, v5, v4
	v_mov_b32_e32 v9, v4
	v_pk_add_f32 v[4:5], v[4:5], v[6:7] neg_lo:[0,1] neg_hi:[0,1]
	s_nop 0
	v_pk_add_f32 v[4:5], v[4:5], v[8:9] neg_lo:[0,1] neg_hi:[0,1]
	s_nop 0
	v_add_f32_e32 v5, v12, v5
	v_add_f32_e32 v4, v4, v5
	v_add_f32_e32 v4, v7, v4
	v_mul_f32_e32 v4, v11, v4
	v_add_f32_e32 v3, v3, v4
	v_add_f32_e32 v4, v14, v3
	v_mul_f32_e32 v6, v4, v4
	v_sub_f32_e32 v7, v4, v14
	v_fmamk_f32 v8, v6, 0x3e9b6dac, v221
	v_sub_f32_e32 v7, v3, v7
	v_mul_f32_e32 v3, v4, v6
	v_fmaak_f32 v201, v6, v8, 0x3f2aaada
	v_ldexp_f32 v9, v7, 1
	v_pk_mul_f32 v[6:7], v[2:3], v[200:201]
	v_ldexp_f32 v5, v4, 1
	v_fma_f32 v4, v2, s2, -v6
	v_fmac_f32_e32 v4, 0xb102e308, v2
	v_pk_add_f32 v[2:3], v[6:7], v[4:5]
	v_mov_b32_e32 v8, v6
	v_sub_f32_e32 v12, v3, v5
	v_pk_add_f32 v[10:11], v[2:3], v[6:7] neg_lo:[0,1] neg_hi:[0,1]
	v_sub_f32_e32 v7, v7, v12
	v_add_f32_e32 v9, v9, v7
	v_pk_add_f32 v[14:15], v[2:3], v[8:9]
	v_mov_b32_e32 v5, v2
	v_mov_b32_e32 v11, v15
	v_pk_add_f32 v[16:17], v[4:5], v[10:11] neg_lo:[0,1] neg_hi:[0,1]
	v_pk_add_f32 v[4:5], v[4:5], v[10:11]
	v_mov_b32_e32 v6, v3
	v_mov_b32_e32 v13, v2
	v_pk_add_f32 v[2:3], v[4:5], v[2:3] op_sel:[1,0] op_sel_hi:[0,1] neg_lo:[0,1] neg_hi:[0,1]
	v_mov_b32_e32 v12, v9
	v_mov_b32_e32 v8, v15
	v_mov_b32_e32 v9, v5
	v_mov_b32_e32 v7, v2
	v_pk_add_f32 v[10:11], v[14:15], v[2:3] op_sel_hi:[1,0] neg_lo:[0,1] neg_hi:[0,1]
	v_pk_add_f32 v[2:3], v[8:9], v[6:7] neg_lo:[0,1] neg_hi:[0,1]
	v_mov_b32_e32 v10, v16
	v_pk_add_f32 v[2:3], v[12:13], v[2:3] neg_lo:[0,1] neg_hi:[0,1]
	v_mov_b32_e32 v17, v5
	v_pk_add_f32 v[6:7], v[10:11], v[2:3]
	s_nop 0
	v_pk_add_f32 v[8:9], v[6:7], v[6:7] op_sel:[0,1] op_sel_hi:[1,0]
	s_nop 0
	v_pk_add_f32 v[4:5], v[4:5], v[8:9] op_sel:[1,0] op_sel_hi:[0,1]
	v_mov_b32_e32 v7, v4
	v_mov_b32_e32 v3, v8
	v_pk_add_f32 v[8:9], v[6:7], v[16:17] neg_lo:[0,1] neg_hi:[0,1]
	s_nop 0
	v_sub_f32_e32 v5, v6, v8
	v_pk_add_f32 v[2:3], v[2:3], v[8:9] neg_lo:[0,1] neg_hi:[0,1]
	v_sub_f32_e32 v5, v16, v5
	v_add_f32_e32 v2, v2, v5
	v_add_f32_e32 v2, v2, v3
	v_add_f32_e32 v2, v4, v2
	v_cndmask_b32_e64 v2, v224, v2, s[68:69]
	v_cmp_lt_f32_e64 s[68:69], |v18|, s3
	s_nop 1
	v_cndmask_b32_e64 v18, v2, v18, s[68:69]
	v_add_f32_e32 v2, -1.0, v20
	v_sub_f32_e32 v3, v2, v20
	v_sub_f32_e32 v2, v19, v2
	v_add_f32_e32 v3, 1.0, v3
	v_add_f32_e32 v2, v2, v3
	v_sub_u32_e32 v3, 0, v21
	v_ldexp_f32 v4, v20, v3
	v_add_f32_e32 v5, -1.0, v4
	v_ldexp_f32 v2, v2, v3
	v_add_f32_e32 v3, 1.0, v5
	v_sub_f32_e32 v3, v4, v3
	v_add_f32_e32 v6, v2, v3
	v_add_f32_e32 v3, 1.0, v4
	v_add_f32_e32 v7, -1.0, v3
	v_sub_f32_e32 v4, v4, v7
	v_add_f32_e32 v2, v2, v4
	v_add_f32_e32 v10, v3, v2
	v_rcp_f32_e32 v12, v10
	v_sub_f32_e32 v3, v3, v10
	v_add_f32_e32 v11, v2, v3
	v_add_f32_e32 v3, v5, v6
	v_mul_f32_e32 v14, v3, v12
	v_sub_f32_e32 v2, v5, v3
	v_mul_f32_e32 v4, v10, v14
	v_add_f32_e32 v13, v6, v2
	v_fma_f32 v6, v14, v10, -v4
	v_fmac_f32_e32 v6, v14, v11
	v_add_f32_e32 v2, v4, v6
	v_sub_f32_e32 v5, v3, v2
	v_pk_add_f32 v[8:9], v[2:3], v[4:5] neg_lo:[0,1] neg_hi:[0,1]
	v_mov_b32_e32 v7, v2
	v_pk_add_f32 v[2:3], v[8:9], v[6:7] neg_lo:[0,1] neg_hi:[0,1]
	v_cmp_neq_f32_e64 s[68:69], s0, v19
	v_add_f32_e32 v3, v13, v3
	v_add_f32_e32 v2, v2, v3
	v_add_f32_e32 v3, v5, v2
	v_mul_f32_e32 v13, v12, v3
	v_mul_f32_e32 v4, v10, v13
	v_fma_f32 v6, v13, v10, -v4
	v_fmac_f32_e32 v6, v13, v11
	v_sub_f32_e32 v5, v5, v3
	v_add_f32_e32 v10, v2, v5
	v_add_f32_e32 v2, v4, v6
	v_sub_f32_e32 v5, v3, v2
	v_pk_add_f32 v[8:9], v[2:3], v[4:5] neg_lo:[0,1] neg_hi:[0,1]
	v_mov_b32_e32 v7, v2
	v_pk_add_f32 v[2:3], v[8:9], v[6:7] neg_lo:[0,1] neg_hi:[0,1]
	v_mul_f32_e32 v110, 0xbfb8aa3b, v18
	v_add_f32_e32 v3, v10, v3
	v_add_f32_e32 v2, v2, v3
	v_add_f32_e32 v3, v14, v13
	v_add_f32_e32 v2, v5, v2
	v_sub_f32_e32 v4, v3, v14
	v_mul_f32_e32 v2, v12, v2
	v_sub_f32_e32 v4, v13, v4
	v_add_f32_e32 v4, v4, v2
	v_add_f32_e32 v6, v3, v4
	v_mul_f32_e32 v7, v6, v6
	v_fmamk_f32 v2, v7, 0x3e9b6dac, v221
	v_fmaak_f32 v201, v7, v2, 0x3f2aaada
	v_cvt_f32_i32_e32 v2, v21
	v_sub_f32_e32 v3, v6, v3
	v_sub_f32_e32 v3, v4, v3
	v_ldexp_f32 v8, v3, 1
	v_mul_f32_e32 v3, v6, v7
	v_ldexp_f32 v5, v6, 1
	v_pk_mul_f32 v[6:7], v[2:3], v[200:201]
	v_mul_f32_e32 v23, v110, v51
	v_fma_f32 v4, v2, s2, -v6
	v_fmac_f32_e32 v4, 0xb102e308, v2
	v_pk_add_f32 v[2:3], v[6:7], v[4:5]
	v_mul_f32_e32 v27, v110, v67
	v_sub_f32_e32 v5, v3, v5
	v_sub_f32_e32 v5, v7, v5
	v_add_f32_e32 v9, v8, v5
	v_mov_b32_e32 v8, v6
	v_pk_add_f32 v[6:7], v[2:3], v[6:7] neg_lo:[0,1] neg_hi:[0,1]
	v_pk_add_f32 v[10:11], v[2:3], v[8:9]
	v_mov_b32_e32 v5, v2
	v_mov_b32_e32 v7, v11
	v_pk_add_f32 v[12:13], v[4:5], v[6:7] neg_lo:[0,1] neg_hi:[0,1]
	v_pk_add_f32 v[4:5], v[4:5], v[6:7]
	v_mov_b32_e32 v16, v3
	v_pk_add_f32 v[6:7], v[4:5], v[2:3] op_sel:[1,0] op_sel_hi:[0,1] neg_lo:[0,1] neg_hi:[0,1]
	v_pk_add_f32 v[14:15], v[10:11], v[6:7] op_sel_hi:[1,0] neg_lo:[0,1] neg_hi:[0,1]
	v_mov_b32_e32 v10, v11
	v_mov_b32_e32 v11, v5
	v_mov_b32_e32 v17, v6
	v_pk_add_f32 v[6:7], v[10:11], v[16:17] neg_lo:[0,1] neg_hi:[0,1]
	v_mov_b32_e32 v8, v9
	v_mov_b32_e32 v9, v2
	v_pk_add_f32 v[2:3], v[8:9], v[6:7] neg_lo:[0,1] neg_hi:[0,1]
	v_mov_b32_e32 v14, v12
	v_pk_add_f32 v[6:7], v[14:15], v[2:3]
	v_mov_b32_e32 v13, v5
	v_pk_add_f32 v[8:9], v[6:7], v[6:7] op_sel:[0,1] op_sel_hi:[1,0]
	v_mul_f32_e32 v122, v110, v99
	v_pk_add_f32 v[4:5], v[4:5], v[8:9] op_sel:[1,0] op_sel_hi:[0,1]
	v_mov_b32_e32 v7, v4
	v_pk_add_f32 v[10:11], v[6:7], v[12:13] neg_lo:[0,1] neg_hi:[0,1]
	v_mov_b32_e32 v3, v8
	v_sub_f32_e32 v5, v6, v10
	v_pk_add_f32 v[2:3], v[2:3], v[10:11] neg_lo:[0,1] neg_hi:[0,1]
	v_sub_f32_e32 v5, v12, v5
	v_add_f32_e32 v2, v2, v5
	v_add_f32_e32 v2, v2, v3
	v_add_f32_e32 v2, v4, v2
	v_cndmask_b32_e64 v2, v224, v2, s[68:69]
	v_cmp_lt_f32_e64 s[68:69], |v19|, s3
	v_readlane_b32 s2, v254, 15
	v_readlane_b32 s3, v254, 16
	v_cndmask_b32_e64 v16, v2, v19, s[68:69]
	v_mul_f32_e32 v2, v110, v42
	v_cmp_gt_f32_e64 s[68:69], s96, v2
	v_lshl_add_u64 v[2:3], s[2:3], 0, v[36:37]
	v_lshl_add_u64 v[0:1], v[0:1], 1, v[2:3]
	v_lshl_add_u64 v[0:1], v[0:1], 0, v[192:193]
	s_waitcnt vmcnt(6)
	v_mov_b32_e32 v4, v176
	v_mov_b32_e32 v5, v177
	v_mov_b32_e32 v6, v178
	v_mov_b32_e32 v7, v179
	s_nop 0
	v_mov_b32_e32 v0, v180
	v_mov_b32_e32 v1, v181
	v_mov_b32_e32 v2, v182
	v_mov_b32_e32 v3, v183
	ds_read2_b64 v[8:11], v39 offset1:1
	ds_read2_b64 v[12:15], v39 offset0:8 offset1:9
	s_waitcnt lgkmcnt(1)
	v_mfma_f32_16x16x32_bf16 v[8:11], v[8:11], v[4:7], 0
	v_mul_f32_e32 v113, 0xbfb8aa3b, v16
	v_readlane_b32 s2, v254, 49
	v_readlane_b32 s3, v254, 50
	s_waitcnt lgkmcnt(0)
	v_mfma_f32_16x16x32_bf16 v[8:11], v[12:15], v[0:3], v[8:11]
	v_mul_f32_e32 v12, v113, v44
	v_mul_f32_e32 v13, v110, v45
	v_cndmask_b32_e64 v12, v13, v12, s[24:25]
	v_exp_f32_e32 v20, v12
	v_mul_f32_e32 v12, v110, v47
	v_mul_f32_e32 v13, v113, v46
	v_cndmask_b32_e64 v12, v12, v13, s[2:3]
	v_exp_f32_e32 v21, v12
	ds_read2_b64 v[12:15], v39 offset0:68 offset1:69
	v_mul_f32_e32 v16, v113, v43
	v_readlane_b32 s2, v254, 51
	v_cndmask_b32_e64 v111, 0, v225, s[68:69]
	v_cndmask_b32_e64 v112, 0, v226, s[68:69]
	v_cmp_gt_f32_e64 s[68:69], s96, v16
	v_mul_f32_e32 v16, v110, v49
	v_mul_f32_e32 v17, v113, v48
	v_readlane_b32 s3, v254, 52
	v_mul_f32_e32 v24, v113, v50
	v_pk_mul_f32 v[28:29], v[8:9], v[20:21]
	v_cndmask_b32_e64 v16, v16, v17, s[2:3]
	v_exp_f32_e32 v22, v16
	ds_read2_b64 v[16:19], v39 offset0:76 offset1:77
	v_readlane_b32 s2, v254, 53
	v_readlane_b32 s3, v254, 54
	s_waitcnt lgkmcnt(1)
	v_mfma_f32_16x16x32_bf16 v[12:15], v[12:15], v[4:7], 0
	v_mul_f32_e32 v20, v113, v58
	v_cndmask_b32_e64 v23, v23, v24, s[2:3]
	v_exp_f32_e32 v23, v23
	v_readlane_b32 s2, v254, 55
	v_readlane_b32 s3, v254, 56
	v_mul_f32_e32 v21, v113, v64
	v_pk_mul_f32 v[116:117], v[10:11], v[22:23]
	s_waitcnt lgkmcnt(0)
	v_mfma_f32_16x16x32_bf16 v[8:11], v[16:19], v[0:3], v[12:15]
	v_mul_f32_e32 v30, v113, v66
	v_mul_f32_e32 v144, v110, v101
	v_mul_f32_e32 v145, v113, v100
	v_mul_f32_e32 v12, v110, v53
	v_mul_f32_e32 v13, v113, v52
	v_cndmask_b32_e64 v12, v12, v13, s[2:3]
	v_readlane_b32 s2, v254, 57
	v_exp_f32_e32 v16, v12
	v_mul_f32_e32 v12, v110, v55
	v_mul_f32_e32 v13, v113, v54
	v_readlane_b32 s3, v254, 58
	v_cndmask_b32_e64 v114, 0, v225, s[68:69]
	v_cndmask_b32_e64 v115, 0, v226, s[68:69]
	v_cndmask_b32_e64 v12, v12, v13, s[2:3]
	v_exp_f32_e32 v17, v12
	v_add_u32_e32 v12, 0x1100, v39
	ds_read2_b64 v[12:15], v12 offset1:1
	v_readlane_b32 s2, v254, 59
	v_pk_mul_f32 v[118:119], v[8:9], v[16:17]
	v_add_u32_e32 v9, 0x1140, v39
	ds_read2_b64 v[16:19], v9 offset1:1
	v_mul_f32_e32 v8, v110, v57
	v_mul_f32_e32 v9, v113, v56
	v_readlane_b32 s3, v254, 60
	s_waitcnt lgkmcnt(1)
	v_mfma_f32_16x16x32_bf16 v[12:15], v[12:15], v[4:7], 0
	v_cndmask_b32_e64 v8, v8, v9, s[2:3]
	v_readlane_b32 s2, v254, 61
	v_mul_f32_e32 v9, v110, v59
	v_readlane_b32 s3, v254, 62
	s_waitcnt lgkmcnt(0)
	v_mfma_f32_16x16x32_bf16 v[12:15], v[16:19], v[0:3], v[12:15]
	v_mul_f32_e32 v16, v110, v61
	v_cndmask_b32_e64 v9, v9, v20, s[2:3]
	v_readlane_b32 s2, v254, 63
	v_mul_f32_e32 v17, v113, v60
	v_readlane_b32 s3, v255, 0
	v_mul_f32_e32 v20, v110, v65
	v_exp_f32_e32 v8, v8
	v_cndmask_b32_e64 v16, v16, v17, s[2:3]
	v_readlane_b32 s2, v255, 1
	v_exp_f32_e32 v24, v16
	v_mul_f32_e32 v16, v110, v63
	v_mul_f32_e32 v17, v113, v62
	v_readlane_b32 s3, v255, 2
	v_exp_f32_e32 v9, v9
	v_fmac_f32_e32 v111, v110, v42
	v_cndmask_b32_e64 v16, v16, v17, s[2:3]
	v_exp_f32_e32 v25, v16
	v_add_u32_e32 v16, 0x1320, v39
	ds_read2_b64 v[16:19], v16 offset1:1
	v_readlane_b32 s2, v255, 3
	v_readlane_b32 s3, v255, 4
	v_pk_mul_f32 v[124:125], v[12:13], v[24:25]
	v_mul_f32_e32 v12, v110, v69
	v_cndmask_b32_e64 v20, v20, v21, s[2:3]
	v_exp_f32_e32 v26, v20
	v_add_u32_e32 v20, 0x1360, v39
	ds_read2_b64 v[20:23], v20 offset1:1
	v_readlane_b32 s2, v255, 5
	s_waitcnt lgkmcnt(1)
	v_mfma_f32_16x16x32_bf16 v[16:19], v[16:19], v[4:7], 0
	v_readlane_b32 s3, v255, 6
	v_mul_f32_e32 v13, v113, v68
	v_cndmask_b32_e64 v12, v12, v13, s[26:27]
	v_cndmask_b32_e64 v27, v27, v30, s[2:3]
	v_exp_f32_e32 v27, v27
	v_pk_mul_f32 v[120:121], v[10:11], v[8:9]
	s_waitcnt lgkmcnt(0)
	v_mfma_f32_16x16x32_bf16 v[8:11], v[20:23], v[0:3], v[16:19]
	v_mul_f32_e32 v13, v113, v70
	v_pk_mul_f32 v[126:127], v[14:15], v[26:27]
	v_mul_f32_e32 v20, v113, v74
	v_exp_f32_e32 v16, v12
	v_mul_f32_e32 v12, v110, v71
	v_cndmask_b32_e64 v12, v12, v13, s[28:29]
	v_exp_f32_e32 v17, v12
	v_add_u32_e32 v12, 0x2200, v39
	ds_read2_b64 v[12:15], v12 offset1:1
	v_mul_f32_e32 v21, v113, v80
	v_pk_mul_f32 v[128:129], v[8:9], v[16:17]
	v_add_u32_e32 v9, 0x2240, v39
	ds_read2_b64 v[16:19], v9 offset1:1
	s_waitcnt lgkmcnt(1)
	v_mfma_f32_16x16x32_bf16 v[12:15], v[12:15], v[4:7], 0
	v_mul_f32_e32 v8, v110, v73
	v_mul_f32_e32 v9, v113, v72
	s_waitcnt lgkmcnt(0)
	v_mfma_f32_16x16x32_bf16 v[12:15], v[16:19], v[0:3], v[12:15]
	v_mul_f32_e32 v16, v110, v77
	v_mul_f32_e32 v17, v113, v76
	v_cndmask_b32_e64 v16, v16, v17, s[36:37]
	v_exp_f32_e32 v24, v16
	v_mul_f32_e32 v16, v110, v79
	v_mul_f32_e32 v17, v113, v78
	v_cndmask_b32_e64 v16, v16, v17, s[38:39]
	v_exp_f32_e32 v25, v16
	v_add_u32_e32 v16, 0x2420, v39
	v_cndmask_b32_e64 v8, v8, v9, s[30:31]
	v_mul_f32_e32 v9, v110, v75
	ds_read2_b64 v[16:19], v16 offset1:1
	v_cndmask_b32_e64 v9, v9, v20, s[34:35]
	v_mul_f32_e32 v20, v110, v81
	v_cndmask_b32_e64 v20, v20, v21, s[40:41]
	v_exp_f32_e32 v26, v20
	v_add_u32_e32 v20, 0x2460, v39
	ds_read2_b64 v[20:23], v20 offset1:1
	v_exp_f32_e32 v8, v8
	v_exp_f32_e32 v9, v9
	s_waitcnt lgkmcnt(1)
	v_mfma_f32_16x16x32_bf16 v[16:19], v[16:19], v[4:7], 0
	v_mul_f32_e32 v27, v110, v83
	v_mul_f32_e32 v30, v113, v82
	v_cndmask_b32_e64 v27, v27, v30, s[42:43]
	v_pk_mul_f32 v[132:133], v[12:13], v[24:25]
	v_mul_f32_e32 v12, v110, v85
	v_mul_f32_e32 v13, v113, v84
	v_exp_f32_e32 v27, v27
	v_cndmask_b32_e64 v12, v12, v13, s[44:45]
	v_pk_mul_f32 v[130:131], v[10:11], v[8:9]
	s_waitcnt lgkmcnt(0)
	v_mfma_f32_16x16x32_bf16 v[8:11], v[20:23], v[0:3], v[16:19]
	v_mul_f32_e32 v13, v113, v86
	v_pk_mul_f32 v[134:135], v[14:15], v[26:27]
	v_mul_f32_e32 v20, v113, v90
	v_exp_f32_e32 v16, v12
	v_mul_f32_e32 v12, v110, v87
	v_cndmask_b32_e64 v12, v12, v13, s[46:47]
	v_exp_f32_e32 v17, v12
	v_add_u32_e32 v12, 0x3300, v39
	ds_read2_b64 v[12:15], v12 offset1:1
	v_mul_f32_e32 v21, v113, v94
	v_pk_mul_f32 v[136:137], v[8:9], v[16:17]
	v_add_u32_e32 v9, 0x3340, v39
	ds_read2_b64 v[16:19], v9 offset1:1
	s_waitcnt lgkmcnt(1)
	v_mfma_f32_16x16x32_bf16 v[12:15], v[12:15], v[4:7], 0
	v_mul_f32_e32 v8, v110, v89
	v_mul_f32_e32 v9, v113, v88
	s_waitcnt lgkmcnt(0)
	v_mfma_f32_16x16x32_bf16 v[12:15], v[16:19], v[0:3], v[12:15]
	v_mul_f32_e32 v16, v110, v93
	v_mul_f32_e32 v17, v113, v92
	v_cndmask_b32_e64 v16, v16, v17, s[76:77]
	v_exp_f32_e32 v138, v16
	v_add_u32_e32 v16, 0x3520, v39
	v_cndmask_b32_e64 v8, v8, v9, s[70:71]
	v_mul_f32_e32 v9, v110, v91
	ds_read2_b64 v[16:19], v16 offset1:1
	v_cndmask_b32_e64 v9, v9, v20, s[74:75]
	v_mul_f32_e32 v20, v110, v95
	v_cndmask_b32_e64 v20, v20, v21, s[78:79]
	v_exp_f32_e32 v139, v20
	v_add_u32_e32 v20, 0x3560, v39
	ds_read2_b64 v[20:23], v20 offset1:1
	s_waitcnt lgkmcnt(1)
	v_mfma_f32_16x16x32_bf16 v[16:19], v[16:19], v[4:7], 0
	v_mul_f32_e32 v24, v110, v97
	v_mul_f32_e32 v25, v113, v96
	v_cndmask_b32_e64 v30, v24, v25, s[80:81]
	s_waitcnt lgkmcnt(0)
	v_mfma_f32_16x16x32_bf16 v[20:23], v[20:23], v[0:3], v[16:19]
	ds_read_b128 v[24:27], v40 offset:17408
	s_nop 1
	v_cvt_pk_bf16_f32 v19, v120, v121
	v_mul_f32_e32 v120, v113, v98
	v_cndmask_b32_e64 v120, v122, v120, s[82:83]
	v_exp_f32_e32 v140, v30
	v_cvt_pk_bf16_f32 v16, v28, v29
	ds_read_b128 v[28:31], v40 offset:21760
	v_cvt_pk_bf16_f32 v17, v116, v117
	v_cvt_pk_bf16_f32 v18, v118, v119
	ds_read_b128 v[116:119], v40 offset:26112
	v_exp_f32_e32 v141, v120
	ds_read_b128 v[120:123], v40 offset:30464
	v_exp_f32_e32 v8, v8
	v_exp_f32_e32 v9, v9
	v_pk_mul_f32 v[138:139], v[12:13], v[138:139]
	v_pk_mul_f32 v[140:141], v[14:15], v[140:141]
	ds_read_b128 v[12:15], v40 offset:17472
	s_waitcnt lgkmcnt(4)
	v_mfma_f32_16x16x32_bf16 v[24:27], v[24:27], v[16:19], 0
	v_mul_f32_e64 v142, v10, v8
	v_mul_f32_e64 v143, v11, v9
	v_fmac_f32_e32 v114, v113, v43
	s_mov_b32 s0, 0x800000
	s_waitcnt lgkmcnt(3)
	v_mfma_f32_16x16x32_bf16 v[28:31], v[28:31], v[16:19], 0
	v_readlane_b32 s2, v254, 19
	v_or_b32_e32 v192, v109, v32
	v_readlane_b32 s3, v254, 20
	s_waitcnt lgkmcnt(2)
	v_mfma_f32_16x16x32_bf16 v[8:11], v[116:119], v[16:19], 0
	v_cvt_pk_bf16_f32 v116, v124, v125
	v_cvt_pk_bf16_f32 v117, v126, v127
	v_cvt_pk_bf16_f32 v118, v128, v129
	s_waitcnt lgkmcnt(1)
	v_mfma_f32_16x16x32_bf16 v[16:19], v[120:123], v[16:19], 0
	ds_read_b128 v[120:123], v40 offset:21824
	v_cvt_pk_bf16_f32 v119, v130, v131
	v_cndmask_b32_e64 v124, v144, v145, s[88:89]
	v_exp_f32_e32 v128, v124
	s_waitcnt lgkmcnt(1)
	v_mfma_f32_16x16x32_bf16 v[12:15], v[12:15], v[116:119], v[24:27]
	v_mul_f32_e32 v124, v110, v103
	v_mul_f32_e32 v125, v113, v102
	v_cndmask_b32_e64 v124, v124, v125, s[90:91]
	ds_read_b128 v[24:27], v40 offset:26176
	s_waitcnt lgkmcnt(1)
	v_mfma_f32_16x16x32_bf16 v[28:31], v[120:123], v[116:119], v[28:31]
	ds_read_b128 v[120:123], v40 offset:30528
	v_mul_f32_e32 v130, v110, v105
	s_waitcnt lgkmcnt(1)
	v_mfma_f32_16x16x32_bf16 v[8:11], v[24:27], v[116:119], v[8:11]
	ds_read_b128 v[24:27], v40 offset:17536
	v_mul_f32_e32 v131, v113, v104
	v_exp_f32_e32 v129, v124
	s_waitcnt lgkmcnt(1)
	v_mfma_f32_16x16x32_bf16 v[116:119], v[120:123], v[116:119], v[16:19]
	v_cvt_pk_bf16_f32 v120, v132, v133
	v_cvt_pk_bf16_f32 v121, v134, v135
	v_cvt_pk_bf16_f32 v122, v136, v137
	ds_read_b128 v[16:19], v40 offset:21888
	v_cvt_pk_bf16_f32 v123, v142, v143
	s_waitcnt lgkmcnt(1)
	s_nop 0
	v_mfma_f32_16x16x32_bf16 v[124:127], v[24:27], v[120:123], v[12:15]
	ds_read_b128 v[24:27], v40 offset:26240
	s_nop 1
	v_cndmask_b32_e64 v12, v130, v131, s[64:65]
	v_exp_f32_e32 v130, v12
	s_waitcnt lgkmcnt(1)
	v_mfma_f32_16x16x32_bf16 v[12:15], v[16:19], v[120:123], v[28:31]
	v_mul_f32_e32 v131, v110, v107
	v_mul_f32_e32 v16, v113, v106
	v_cndmask_b32_e64 v16, v131, v16, s[66:67]
	ds_read_b128 v[28:31], v40 offset:30592
	v_exp_f32_e32 v131, v16
	s_waitcnt lgkmcnt(1)
	v_mfma_f32_16x16x32_bf16 v[16:19], v[24:27], v[120:123], v[8:11]
	v_mul_f32_e64 v26, v20, v128
	v_mul_f32_e64 v27, v21, v129
	v_pk_mul_f32 v[128:129], v[22:23], v[130:131]
	v_cvt_pk_bf16_f32 v24, v138, v139
	ds_read_b128 v[8:11], v40 offset:17600
	s_waitcnt lgkmcnt(1)
	v_mfma_f32_16x16x32_bf16 v[20:23], v[28:31], v[120:123], v[116:119]
	ds_read_b128 v[28:31], v40 offset:21952
	v_cvt_pk_bf16_f32 v25, v140, v141
	s_nop 0
	v_add_u32_e32 v116, 64, v242
	v_cvt_pk_bf16_f32 v26, v26, v27
	v_cvt_pk_bf16_f32 v27, v128, v129
	v_cmp_lt_i32_e64 s[68:69], v237, v116
	v_exp_f32_e32 v110, v111
	s_waitcnt lgkmcnt(0)
	v_mfma_f32_16x16x32_bf16 v[12:15], v[28:31], v[24:27], v[12:15]
	v_cndmask_b32_e64 v144, v220, v237, s[68:69]
	v_cmp_lt_i32_e64 s[68:69], v236, v116
	ds_read_b128 v[28:31], v40 offset:26304
	ds_read_b128 v[116:119], v40 offset:30656
	s_waitcnt lgkmcnt(1)
	v_mfma_f32_16x16x32_bf16 v[16:19], v[28:31], v[24:27], v[16:19]
	ds_read_b128 v[28:31], v41 offset:34816
	ds_read_b128 v[120:123], v41 offset:37120
	ds_read_b128 v[128:131], v41 offset:39424
	v_mfma_f32_16x16x32_bf16 v[8:11], v[8:11], v[24:27], v[124:127]
	ds_read_b128 v[132:135], v41 offset:48640
	ds_read_b128 v[136:139], v41 offset:41728
	ds_read_b128 v[140:143], v41 offset:50944
	s_waitcnt lgkmcnt(6)
	v_mfma_f32_16x16x32_bf16 v[20:23], v[116:119], v[24:27], v[20:23]
	ds_read_b128 v[24:27], v41 offset:34880
	ds_read_b128 v[116:119], v41 offset:44032
	ds_read_b128 v[124:127], v41 offset:46336
	s_waitcnt lgkmcnt(8)
	v_mfma_f32_16x16x32_bf16 v[28:31], v[28:31], v[4:7], 0
	v_exp_f32_e32 v111, v114
	v_cndmask_b32_e64 v145, v220, v236, s[68:69]
	s_waitcnt lgkmcnt(2)
	v_mfma_f32_16x16x32_bf16 v[24:27], v[24:27], v[0:3], v[28:31]
	s_nop 3
	ds_read_b128 v[28:31], v41 offset:44096
	s_waitcnt lgkmcnt(2)
	v_mfma_f32_16x16x32_bf16 v[116:119], v[116:119], v[4:7], 0
	s_waitcnt lgkmcnt(0)
	v_mfma_f32_16x16x32_bf16 v[28:31], v[28:31], v[0:3], v[116:119]
	s_nop 5
	ds_read_b128 v[116:119], v41 offset:37184
	v_mfma_f32_16x16x32_bf16 v[120:123], v[120:123], v[4:7], 0
	s_waitcnt lgkmcnt(0)
	v_mfma_f32_16x16x32_bf16 v[116:119], v[116:119], v[0:3], v[120:123]
	s_nop 5
	ds_read_b128 v[120:123], v41 offset:46400
	v_mfma_f32_16x16x32_bf16 v[124:127], v[124:127], v[4:7], 0
	s_waitcnt lgkmcnt(0)
	v_mfma_f32_16x16x32_bf16 v[120:123], v[120:123], v[0:3], v[124:127]
	s_nop 5
	ds_read_b128 v[124:127], v41 offset:39488
	v_mfma_f32_16x16x32_bf16 v[128:131], v[128:131], v[4:7], 0
	s_waitcnt lgkmcnt(0)
	v_mfma_f32_16x16x32_bf16 v[124:127], v[124:127], v[0:3], v[128:131]
	s_nop 5
	ds_read_b128 v[128:131], v41 offset:48704
	v_mfma_f32_16x16x32_bf16 v[132:135], v[132:135], v[4:7], 0
	s_waitcnt lgkmcnt(0)
	v_mfma_f32_16x16x32_bf16 v[128:131], v[128:131], v[0:3], v[132:135]
	s_nop 5
	ds_read_b128 v[132:135], v41 offset:41792
	v_mfma_f32_16x16x32_bf16 v[136:139], v[136:139], v[4:7], 0
	s_waitcnt lgkmcnt(0)
	v_mfma_f32_16x16x32_bf16 v[132:135], v[132:135], v[0:3], v[136:139]
	s_nop 5
	ds_read_b128 v[136:139], v41 offset:51008
	v_mfma_f32_16x16x32_bf16 v[4:7], v[140:143], v[4:7], 0
	s_waitcnt lgkmcnt(0)
	v_mfma_f32_16x16x32_bf16 v[0:3], v[136:139], v[0:3], v[4:7]
	s_nop 5
	v_ldexp_f32 v6, v111, v115
	v_ldexp_f32 v4, v110, v112
	v_pk_mul_f32 v[110:111], v[6:7], v[128:129] op_sel_hi:[0,1]
	v_pk_mul_f32 v[0:1], v[6:7], v[0:1] op_sel_hi:[0,1]
	v_pk_fma_f32 v[0:1], v[4:5], v[132:133], v[0:1] op_sel_hi:[0,1,1]
	v_pk_add_f32 v[0:1], v[20:21], v[0:1]
	v_pk_mul_f32 v[20:21], v[6:7], v[122:123] op_sel_hi:[0,1]
	v_pk_fma_f32 v[20:21], v[4:5], v[118:119], v[20:21] op_sel_hi:[0,1,1]
	v_pk_add_f32 v[14:15], v[14:15], v[20:21]
	v_pk_mul_f32 v[20:21], v[6:7], v[120:121] op_sel_hi:[0,1]
	v_pk_fma_f32 v[110:111], v[4:5], v[124:125], v[110:111] op_sel_hi:[0,1,1]
	v_pk_fma_f32 v[20:21], v[4:5], v[116:117], v[20:21] op_sel_hi:[0,1,1]
	v_pk_add_f32 v[16:17], v[16:17], v[110:111]
	v_pk_mul_f32 v[110:111], v[6:7], v[130:131] op_sel_hi:[0,1]
	v_pk_mul_f32 v[2:3], v[6:7], v[2:3] op_sel_hi:[0,1]
	v_pk_add_f32 v[12:13], v[12:13], v[20:21]
	v_pk_mul_f32 v[20:21], v[6:7], v[30:31] op_sel_hi:[0,1]
	v_pk_mul_f32 v[6:7], v[6:7], v[28:29] op_sel_hi:[0,1]
	v_pk_fma_f32 v[110:111], v[4:5], v[126:127], v[110:111] op_sel_hi:[0,1,1]
	v_pk_fma_f32 v[2:3], v[4:5], v[134:135], v[2:3] op_sel_hi:[0,1,1]
	v_pk_fma_f32 v[20:21], v[4:5], v[26:27], v[20:21] op_sel_hi:[0,1,1]
	v_pk_fma_f32 v[4:5], v[4:5], v[24:25], v[6:7] op_sel_hi:[0,1,1]
	v_pk_add_f32 v[4:5], v[8:9], v[4:5]
	v_pk_add_f32 v[10:11], v[10:11], v[20:21]
	v_add_f32_e32 v6, 0, v4
	v_add_f32_e32 v6, v5, v6
	v_add_f32_e32 v6, v10, v6
	v_add_f32_e32 v6, v11, v6
	v_add_f32_e32 v6, v6, v12
	v_add_f32_e32 v6, v13, v6
	v_add_f32_e32 v6, v14, v6
	v_add_f32_e32 v6, v15, v6
	v_add_f32_e32 v6, v6, v16
	v_pk_add_f32 v[18:19], v[18:19], v[110:111]
	v_add_f32_e32 v6, v17, v6
	v_add_f32_e32 v6, v18, v6
	v_add_f32_e32 v6, v19, v6
	v_add_f32_e32 v6, v6, v0
	v_pk_add_f32 v[2:3], v[22:23], v[2:3]
	v_add_f32_e32 v6, v1, v6
	v_add_f32_e32 v6, v2, v6
	v_lshlrev_b32_e32 v110, 2, v144
	v_add_f32_e32 v6, v3, v6
	ds_bpermute_b32 v7, v110, v6
	v_lshlrev_b32_e32 v111, 2, v145
	s_waitcnt lgkmcnt(0)
	v_add_f32_e32 v6, v6, v7
	ds_bpermute_b32 v7, v111, v6
	s_waitcnt lgkmcnt(0)
	v_add_f32_e32 v6, v6, v7
	v_mul_f32_e32 v6, 0x3c800000, v6
	v_pk_add_f32 v[20:21], v[4:5], v[6:7] op_sel_hi:[1,0] neg_lo:[0,1] neg_hi:[0,1]
	v_pk_add_f32 v[22:23], v[10:11], v[6:7] op_sel_hi:[1,0] neg_lo:[0,1] neg_hi:[0,1]
	v_pk_mul_f32 v[4:5], v[20:21], v[20:21]
	v_pk_mul_f32 v[8:9], v[22:23], v[22:23]
	v_add_f32_e32 v4, v4, v5
	v_pk_add_f32 v[12:13], v[12:13], v[6:7] op_sel_hi:[1,0] neg_lo:[0,1] neg_hi:[0,1]
	v_add_f32_e32 v4, v8, v4
	v_pk_mul_f32 v[10:11], v[12:13], v[12:13]
	v_add_f32_e32 v4, v9, v4
	v_pk_add_f32 v[14:15], v[14:15], v[6:7] op_sel_hi:[1,0] neg_lo:[0,1] neg_hi:[0,1]
	v_add_f32_e32 v4, v10, v4
	v_pk_mul_f32 v[24:25], v[14:15], v[14:15]
	v_add_f32_e32 v4, v11, v4
	v_pk_add_f32 v[16:17], v[16:17], v[6:7] op_sel_hi:[1,0] neg_lo:[0,1] neg_hi:[0,1]
	v_add_f32_e32 v4, v24, v4
	v_pk_add_f32 v[26:27], v[0:1], v[6:7] op_sel_hi:[1,0] neg_lo:[0,1] neg_hi:[0,1]
	v_pk_add_f32 v[28:29], v[2:3], v[6:7] op_sel_hi:[1,0] neg_lo:[0,1] neg_hi:[0,1]
	v_pk_add_f32 v[18:19], v[18:19], v[6:7] op_sel_hi:[1,0] neg_lo:[0,1] neg_hi:[0,1]
	v_pk_mul_f32 v[6:7], v[16:17], v[16:17]
	v_add_f32_e32 v4, v25, v4
	v_add_f32_e32 v4, v6, v4
	v_pk_mul_f32 v[30:31], v[18:19], v[18:19]
	v_add_f32_e32 v4, v7, v4
	v_add_f32_e32 v4, v30, v4
	v_pk_mul_f32 v[0:1], v[26:27], v[26:27]
	v_add_f32_e32 v4, v31, v4
	v_add_f32_e32 v0, v0, v4
	v_pk_mul_f32 v[2:3], v[28:29], v[28:29]
	v_add_f32_e32 v0, v1, v0
	v_add_f32_e32 v0, v2, v0
	v_add_f32_e32 v0, v3, v0
	ds_bpermute_b32 v1, v110, v0
	v_lshlrev_b64 v[30:31], 1, v[192:193]
	s_waitcnt lgkmcnt(0)
	v_add_f32_e32 v0, v0, v1
	ds_bpermute_b32 v1, v111, v0
	v_lshl_add_u64 v[110:111], v[192:193], 2, s[92:93]
	s_waitcnt lgkmcnt(0)
	v_add_f32_e32 v0, v0, v1
	v_fmamk_f32 v0, v0, 0x3c800000, v194
	v_mul_f32_e32 v1, 0x4b800000, v0
	v_cmp_gt_f32_e64 s[68:69], s0, v0
	v_readlane_b32 s0, v253, 0
	s_add_i32 s97, s97, s0
	v_cndmask_b32_e64 v0, v0, v1, s[68:69]
	v_rsq_f32_e32 v0, v0
	s_cmpk_gt_i32 s97, 0x9ff
	v_mul_f32_e32 v1, 0x45800000, v0
	v_cndmask_b32_e64 v24, v0, v1, s[68:69]
	v_lshl_add_u64 v[0:1], s[2:3], 0, v[36:37]
	v_lshl_add_u64 v[36:37], v[0:1], 0, v[30:31]
	v_mov_b32_e32 v0, v184
	v_mov_b32_e32 v1, v185
	v_mov_b32_e32 v2, v186
	v_mov_b32_e32 v3, v187
	v_mov_b32_e32 v4, v208
	v_mov_b32_e32 v5, v209
	v_mov_b32_e32 v6, v210
	v_mov_b32_e32 v7, v211
	v_mov_b32_e32 v8, v212
	v_mov_b32_e32 v9, v213
	v_mov_b32_e32 v10, v214
	v_mov_b32_e32 v11, v215
	v_readlane_b32 s2, v254, 21
	v_readlane_b32 s3, v254, 22
	v_lshlrev_b32_e32 v112, 16, v0
	v_and_b32_e32 v113, 0xffff0000, v0
	v_lshlrev_b32_e32 v114, 16, v1
	v_and_b32_e32 v115, 0xffff0000, v1
	v_lshlrev_b32_e32 v116, 16, v2
	v_and_b32_e32 v117, 0xffff0000, v2
	v_lshlrev_b32_e32 v118, 16, v3
	v_and_b32_e32 v119, 0xffff0000, v3
	v_pk_mul_f32 v[0:1], v[20:21], v[24:25] op_sel_hi:[1,0]
	v_pk_mul_f32 v[2:3], v[22:23], v[24:25] op_sel_hi:[1,0]
	v_pk_mul_f32 v[0:1], v[4:5], v[0:1]
	v_pk_mul_f32 v[2:3], v[6:7], v[2:3]
	v_pk_mul_f32 v[0:1], v[0:1], v[112:113]
	v_pk_mul_f32 v[2:3], v[2:3], v[114:115]
	v_cvt_pk_bf16_f32 v0, v0, v1
	v_cvt_pk_bf16_f32 v1, v2, v3
	v_pk_mul_f32 v[2:3], v[12:13], v[24:25] op_sel_hi:[1,0]
	v_pk_mul_f32 v[4:5], v[14:15], v[24:25] op_sel_hi:[1,0]
	v_pk_mul_f32 v[2:3], v[8:9], v[2:3]
	v_pk_mul_f32 v[4:5], v[10:11], v[4:5]
	v_lshl_add_u64 v[34:35], s[2:3], 0, v[34:35]
	v_pk_mul_f32 v[2:3], v[2:3], v[116:117]
	v_pk_mul_f32 v[4:5], v[4:5], v[118:119]
	v_lshl_add_u64 v[30:31], v[34:35], 0, v[30:31]
	v_cvt_pk_bf16_f32 v2, v2, v3
	v_cvt_pk_bf16_f32 v3, v4, v5
	global_store_dwordx4 v[30:31], v[0:3], off
	s_nop 1
	v_mov_b32_e32 v0, v188
	v_mov_b32_e32 v1, v189
	v_mov_b32_e32 v2, v190
	v_mov_b32_e32 v3, v191
	s_nop 0
	v_mov_b32_e32 v4, v216
	v_mov_b32_e32 v5, v217
	v_mov_b32_e32 v6, v218
	v_mov_b32_e32 v7, v219
	v_mov_b32_e32 v8, v244
	v_mov_b32_e32 v9, v245
	v_mov_b32_e32 v10, v246
	v_mov_b32_e32 v11, v247
	v_pk_mul_f32 v[14:15], v[16:17], v[24:25] op_sel_hi:[1,0]
	v_lshlrev_b32_e32 v12, 16, v0
	v_pk_mul_f32 v[4:5], v[4:5], v[14:15]
	v_and_b32_e32 v13, 0xffff0000, v0
	v_pk_mul_f32 v[4:5], v[4:5], v[12:13]
	v_pk_mul_f32 v[12:13], v[18:19], v[24:25] op_sel_hi:[1,0]
	v_cvt_pk_bf16_f32 v0, v4, v5
	v_lshlrev_b32_e32 v4, 16, v1
	v_pk_mul_f32 v[6:7], v[6:7], v[12:13]
	v_and_b32_e32 v5, 0xffff0000, v1
	v_pk_mul_f32 v[4:5], v[6:7], v[4:5]
	v_pk_mul_f32 v[6:7], v[26:27], v[24:25] op_sel_hi:[1,0]
	v_cvt_pk_bf16_f32 v1, v4, v5
	v_lshlrev_b32_e32 v4, 16, v2
	v_and_b32_e32 v5, 0xffff0000, v2
	v_pk_mul_f32 v[6:7], v[8:9], v[6:7]
	s_nop 0
	v_pk_mul_f32 v[4:5], v[6:7], v[4:5]
	v_pk_mul_f32 v[6:7], v[28:29], v[24:25] op_sel_hi:[1,0]
	v_cvt_pk_bf16_f32 v2, v4, v5
	v_lshlrev_b32_e32 v4, 16, v3
	v_and_b32_e32 v5, 0xffff0000, v3
	v_pk_mul_f32 v[6:7], v[10:11], v[6:7]
	s_nop 0
	v_pk_mul_f32 v[4:5], v[6:7], v[4:5]
	s_nop 0
	v_cvt_pk_bf16_f32 v3, v4, v5
	global_store_dwordx4 v[30:31], v[0:3], off offset:64
	s_barrier
	s_cbranch_scc1 .LBB0_873
.LBB0_860:
	s_and_b32 s14, s97, 3
	s_lshl_b32 s4, s97, 5
	s_and_b32 vcc_lo, s4, 0xffffff80
	s_lshl_b32 s0, s14, 6
	v_lshrrev_b32_e32 v0, 3, v33
	v_and_b32_e32 v1, 7, v33
	v_lshlrev_b32_e32 v2, 4, v1
	v_lshl_add_u32 v146, v0, 9, v2
	v_add_u32_e32 v147, 0x8000, v146
	v_mad_u32_u24 v176, v0, s18, v2
	v_and_b32_e32 v3, 32, v0
	v_bfe_u32 v1, v0, 2, 1
	v_lshl_or_b32 v3, v1, 4, v3
	v_bfe_u32 v1, v0, 3, 2
	v_lshl_or_b32 v3, v1, 2, v3
	v_and_b32_e32 v1, 3, v0
	v_or_b32_e32 v3, v3, v1
	v_mul_u32_u24_e32 v3, 0x90, v3
	v_add_u32_e32 v178, v3, v2
	v_lshlrev_b32_e32 v248, 4, v33
	v_add_u32_e32 v249, 0x2000, v248
	v_lshrrev_b32_e32 v0, 4, v33
	v_and_b32_e32 v1, 15, v33
	v_lshlrev_b32_e32 v2, 4, v1
	v_add_u32_e32 v3, s0, v0
	v_mul_u32_u24_e32 v3, 0x28000, v3
	v_add_u32_e32 v206, v3, v2
	v_add_u32_e32 v207, 0x500000, v206
	v_bfe_u32 v1, v0, 2, 1
	v_lshlrev_b32_e32 v3, 4, v1
	v_bfe_u32 v1, v0, 3, 2
	v_lshl_or_b32 v3, v1, 2, v3
	v_and_b32_e32 v1, 3, v0
	v_or_b32_e32 v3, v3, v1
	v_mul_u32_u24_e32 v3, 0x110, v3
	v_add_u32_e32 v177, v3, v2
	v_readlane_b32 s6, v254, 17
	v_readlane_b32 s7, v254, 18
	s_lshl_b32 s4, vcc_lo, 9
	s_lshl_b32 s5, s14, 7
	s_add_u32 s4, s4, s5
	s_add_u32 s6, s6, s4
	s_addc_u32 s7, s7, 0
	v_readlane_b32 s4, v253, 54
	v_readlane_b32 s5, v253, 55
	s_lshl_b32 s8, vcc_lo, 1
	s_add_u32 s4, s4, s8
	s_addc_u32 s5, s5, 0
	v_readlane_b32 s8, v254, 6
	v_readlane_b32 s9, v254, 7
	s_lshl_b32 s15, s97, 14
	s_add_u32 s8, s8, s15
	s_addc_u32 s9, s9, 0
	v_readlane_b32 s98, v253, 5
	s_nop 1
	s_cmp_lg_u32 s97, s98
	s_cbranch_scc1 .Lro_have
	global_load_dwordx4 v[148:151], v146, s[6:7]
	global_load_dwordx4 v[152:155], v147, s[6:7]
	global_load_dwordx4 v[156:159], v206, s[4:5]
	global_load_dwordx4 v[160:163], v207, s[4:5]
	global_load_dwordx4 v[164:167], v248, s[8:9]
	global_load_dwordx4 v[168:171], v249, s[8:9]
.Lro_have:
	v_mov_b32_e32 v109, s0
	s_waitcnt vmcnt(0)
	ds_write_b64 v176, v[148:149]
	ds_write_b64 v176, v[150:151] offset:8
	ds_write_b64 v176, v[152:153] offset:8704
	ds_write_b64 v176, v[154:155] offset:8712
	ds_write_b128 v177, v[156:159] offset:17408
	ds_write_b128 v177, v[160:163] offset:26112
	ds_write_b128 v178, v[164:167] offset:34816
	ds_write_b128 v178, v[168:171] offset:44032
	v_mov_b32_e32 v0, s0
	v_mov_b32_e32 v1, 0
	s_branch .Lro_compute
